# barrier 1 split-phase with rotary-table generation inside its wait window; first final-attention item loads its merge operands (and waits for barrier 5) after the first key tile
# speedup vs baseline: 1.0554x; 1.0038x over previous
.LBB0_30:
	s_or_b64 exec, exec, s[10:11]
	v_cvt_f32_u32_e32 v5, v3
	s_waitcnt vmcnt(0)
	v_readfirstlane_b32 s7, v4
	v_sub_u32_e32 v4, 0, v3
	v_rcp_iflag_f32_e32 v5, v5
	v_add_u32_e32 v6, s7, v2
	v_mul_f32_e32 v5, 0x4f7ffffe, v5
	v_cvt_u32_f32_e32 v5, v5
	v_mul_lo_u32 v2, v4, v5
	v_mul_hi_u32 v2, v5, v2
	v_add_u32_e32 v2, v5, v2
	v_mul_hi_u32 v2, v6, v2
	v_mul_lo_u32 v4, v2, v3
	v_sub_u32_e32 v4, v6, v4
	v_add_u32_e32 v5, 1, v2
	v_cmp_ge_u32_e32 vcc, v4, v3
	s_nop 1
	v_cndmask_b32_e32 v2, v2, v5, vcc
	v_sub_u32_e32 v5, v4, v3
	v_cndmask_b32_e32 v4, v4, v5, vcc
	v_add_u32_e32 v5, 1, v2
	v_cmp_ge_u32_e32 vcc, v4, v3
	v_add_u32_e32 v4, 1, v6
	s_nop 0
	v_cndmask_b32_e32 v2, v2, v5, vcc
	v_mul_lo_u32 v5, v3, v2
	v_add_u32_e32 v3, v5, v3
	v_cmp_ne_u32_e32 vcc, v4, v3
	s_and_saveexec_b64 s[8:9], vcc
	s_xor_b64 s[8:9], exec, s[8:9]
	s_cbranch_execz .LBB0_44
	s_waitcnt lgkmcnt(0)
	v_mov_b32_e32 v1, 0x7000
	buffer_inv sc1
	s_branch .Lsplit1_nl
	global_load_dword v1, v1, s[82:83] offset:1280 sc1
	s_add_u32 s14, s82, 0x7500
	s_addc_u32 s15, s83, 0
	s_waitcnt vmcnt(0)
	v_cmp_eq_u32_e32 vcc, v1, v2
	s_and_saveexec_b64 s[10:11], vcc
	s_cbranch_execz .LBB0_43
	s_add_u32 s12, s82, 0x4200
	s_addc_u32 s13, s83, 0
	s_mov_b32 s7, 1
	s_mov_b64 s[16:17], 0
	v_mov_b32_e32 v1, 0
	s_branch .LBB0_34

.Lsplit1_nl:
.LBB0_44:
	s_andn2_saveexec_b64 s[8:9], s[8:9]
	s_cbranch_execz .LBB0_64
	s_mov_b64 s[8:9], exec
	buffer_wbl2 sc1
	buffer_inv sc1
	s_waitcnt lgkmcnt(0)
	s_waitcnt vmcnt(0)
	v_mbcnt_lo_u32_b32 v2, s8, 0
	v_mbcnt_hi_u32_b32 v2, s9, v2
	v_cmp_eq_u32_e32 vcc, 0, v2
	s_and_saveexec_b64 s[10:11], vcc
	s_cbranch_execz .LBB0_47
	s_bcnt1_i32_b64 s7, s[8:9]
	v_mov_b32_e32 v3, 0x7000
	v_mov_b32_e32 v4, s7
	global_atomic_add v3, v3, v4, s[82:83] offset:1024 sc0
.LBB0_47:
	s_or_b64 exec, exec, s[10:11]
	v_cvt_f32_u32_e32 v4, v1
	s_waitcnt vmcnt(0)
	v_readfirstlane_b32 s7, v3
	s_add_u32 s10, s82, 0x7500
	s_addc_u32 s11, s83, 0
	v_rcp_iflag_f32_e32 v4, v4
	v_add_u32_e32 v2, s7, v2
	v_add_u32_e32 v5, 1, v2
	s_mov_b64 s[12:13], -1
	v_mul_f32_e32 v3, 0x4f7ffffe, v4
	v_cvt_u32_f32_e32 v3, v3
	v_sub_u32_e32 v4, 0, v1
	v_mul_lo_u32 v4, v4, v3
	v_mul_hi_u32 v4, v3, v4
	v_add_u32_e32 v3, v3, v4
	v_mul_hi_u32 v3, v2, v3
	v_mul_lo_u32 v4, v3, v1
	v_sub_u32_e32 v2, v2, v4
	v_add_u32_e32 v6, 1, v3
	v_cmp_ge_u32_e32 vcc, v2, v1
	v_sub_u32_e32 v4, v2, v1
	s_nop 0
	v_cndmask_b32_e32 v3, v3, v6, vcc
	v_cndmask_b32_e32 v2, v2, v4, vcc
	v_add_u32_e32 v4, 1, v3
	v_cmp_ge_u32_e32 vcc, v2, v1
	s_nop 1
	v_cndmask_b32_e32 v4, v3, v4, vcc
	v_mul_lo_u32 v2, v1, v4
	v_add_u32_e32 v1, v2, v1
	v_cmp_ne_u32_e32 vcc, v5, v1
	v_mov_b64_e32 v[2:3], s[10:11]
	s_and_saveexec_b64 s[8:9], vcc
	s_cbranch_execz .LBB0_59
	s_mov_b64 s[16:17], 0
	s_branch .Lsplit1_ld
	v_mov_b32_e32 v1, 0
	global_load_dword v2, v1, s[10:11] sc1
	s_mov_b64 s[16:17], 0
	s_waitcnt vmcnt(0)
	v_cmp_eq_u32_e32 vcc, v2, v4
	s_and_saveexec_b64 s[14:15], vcc
	s_cbranch_execz .LBB0_58
	s_add_u32 s12, s82, 0x4200
	s_addc_u32 s13, s83, 0
	s_mov_b32 s7, 1
	s_branch .LBB0_51

.Lsplit1_ld:
	v_mov_b64_e32 v[2:3], s[12:13]
	s_orn2_b64 s[12:13], s[16:17], exec

.LBB0_64:
	s_or_b64 exec, exec, s[0:1]
	v_and_b32_e32 v240, 31, v0
	v_add_u32_e32 v250, s33, v0
	v_ashrrev_i32_e32 v251, 31, v250
	s_mov_b32 s20, 0x80000
	v_cmp_gt_i32_e32 vcc, s20, v250
	s_and_saveexec_b64 s[20:21], vcc
	s_cbranch_execz .Lrope_done
	s_mov_b32 s22, 0x979a371
	v_cvt_f64_u32_e32 v[240:241], v240
	s_mov_b32 s23, 0xbfda934f
	v_mul_f64 v[240:241], v[240:241], s[22:23]
	v_rndne_f64_e32 v[242:243], v[240:241]
	s_mov_b32 s22, 0x3b39803f
	v_add_f64 v[244:245], v[240:241], -v[242:243]
	s_mov_b32 s23, 0x3c7abc9e
	v_mul_f64 v[246:247], v[244:245], s[22:23]
	s_mov_b32 s22, 0xfefa39ef
	s_mov_b32 s23, 0x3fe62e42
	v_fmac_f64_e32 v[246:247], s[22:23], v[244:245]
	s_mov_b32 s22, 0x6a5dcb37
	v_mov_b32_e32 v244, 0xfca7ab0c
	v_mov_b32_e32 v245, 0x3e928af3
	s_mov_b32 s23, 0x3e5ade15
	v_fmac_f64_e32 v[244:245], s[22:23], v[246:247]
	v_mov_b32_e32 v248, 0x623fde64
	v_mov_b32_e32 v249, 0x3ec71dee
	v_fmac_f64_e32 v[248:249], v[246:247], v[244:245]
	v_mov_b32_e32 v244, 0x7c89e6b0
	v_mov_b32_e32 v245, 0x3efa0199
	v_fmac_f64_e32 v[244:245], v[246:247], v[248:249]
	v_mov_b32_e32 v248, 0x14761f6e
	v_mov_b32_e32 v249, 0x3f2a01a0
	v_fmac_f64_e32 v[248:249], v[246:247], v[244:245]
	v_mov_b32_e32 v244, 0x1852b7b0
	v_mov_b32_e32 v245, 0x3f56c16c
	v_fmac_f64_e32 v[244:245], v[246:247], v[248:249]
	v_mov_b32_e32 v248, 0x11122322
	v_mov_b32_e32 v249, 0x3f811111
	v_fmac_f64_e32 v[248:249], v[246:247], v[244:245]
	v_mov_b32_e32 v244, 0x555502a1
	v_mov_b32_e32 v245, 0x3fa55555
	v_fmac_f64_e32 v[244:245], v[246:247], v[248:249]
	v_mov_b32_e32 v248, 0x55555511
	v_mov_b32_e32 v249, 0x3fc55555
	v_fmac_f64_e32 v[248:249], v[246:247], v[244:245]
	v_mov_b32_e32 v244, 11
	v_mov_b32_e32 v245, 0x3fe00000
	s_mov_b32 s22, 0
	v_fmac_f64_e32 v[244:245], v[246:247], v[248:249]
	s_mov_b32 s23, 0x40900000
	v_fma_f64 v[244:245], v[246:247], v[244:245], 1.0
	v_cmp_nlt_f64_e32 vcc, s[22:23], v[240:241]
	s_mov_b32 s22, 0
	v_fma_f64 v[244:245], v[246:247], v[244:245], 1.0
	v_cvt_i32_f64_e32 v242, v[242:243]
	s_mov_b32 s23, 0xc090cc00
	v_ldexp_f64 v[242:243], v[244:245], v242
	v_mov_b32_e32 v244, 0x7ff00000
	v_cmp_ngt_f64_e64 s[22:23], s[22:23], v[240:241]
	v_cndmask_b32_e32 v243, v244, v243, vcc
	s_and_b64 vcc, s[22:23], vcc
	v_cndmask_b32_e64 v241, 0, v243, s[22:23]
	v_cndmask_b32_e32 v240, 0, v242, vcc
	v_cvt_f32_f64_e32 v242, v[240:241]
	v_lshl_add_u64 v[240:241], v[250:251], 2, s[82:83]
	s_mov_b64 s[22:23], 0xc00000
	s_mov_b32 s26, s6
	s_ashr_i32 s27, s6, 31
	s_mov_b32 s28, 0x6dc9c883
	v_lshl_add_u64 v[240:241], v[240:241], 0, s[22:23]
	s_lshl_b64 s[22:23], s[26:27], 2
	s_mov_b64 s[24:25], 0
	s_mov_b32 s29, 0x3fc45f30
	s_mov_b32 s30, 0x7ffff
	s_add_u32 s98, s82, 0xc00000
	s_addc_u32 s99, s83, 0
	s_add_u32 s100, s82, 0xe00000
	s_addc_u32 s101, s83, 0
.Lrope_loop:
	v_and_b32_e32 v232, 0xfffffe03, v250
	v_bfe_u32 v233, v250, 5, 4
	v_lshl_or_b32 v232, v233, 2, v232
	v_bfe_u32 v233, v250, 3, 2
	v_lshl_or_b32 v232, v233, 6, v232
	v_bfe_u32 v233, v250, 2, 1
	v_lshl_or_b32 v232, v233, 8, v232
	v_lshlrev_b32_e32 v232, 2, v232
	v_ashrrev_i32_e32 v244, 5, v250
	v_ashrrev_i32_e32 v245, 31, v244
	v_lshl_add_u64 v[244:245], v[244:245], 2, s[48:49]
	global_load_dword v243, v[244:245], off
	v_add_co_u32_e32 v244, vcc, 0x200000, v240
	v_add_u32_e32 v250, s6, v250
	s_nop 0
	v_addc_co_u32_e32 v245, vcc, 0, v241, vcc
	v_cmp_lt_i32_e32 vcc, s30, v250
	s_or_b64 s[24:25], vcc, s[24:25]
	s_waitcnt vmcnt(0)
	v_cvt_f32_i32_e32 v243, v243
	v_mul_f32_e32 v243, v242, v243
	v_cvt_f64_f32_e32 v[246:247], v243
	v_mul_f64 v[248:249], v[246:247], s[28:29]
	v_rndne_f64_e32 v[248:249], v[248:249]
	v_fma_f64 v[246:247], v[246:247], s[28:29], -v[248:249]
	v_cvt_f32_f64_e32 v243, v[246:247]
	v_cos_f32_e32 v246, v243
	v_sin_f32_e32 v243, v243
	global_store_dword v232, v246, s[98:99]
	global_store_dword v232, v243, s[100:101]
	v_lshl_add_u64 v[240:241], v[240:241], 0, s[22:23]
	s_andn2_b64 exec, exec, s[24:25]
	s_cbranch_execnz .Lrope_loop
.Lrope_done:
	s_or_b64 exec, exec, s[20:21]
	s_mov_b64 s[20:21], exec
	v_readlane_b32 s22, v254, 6
	s_nop 3
	s_mov_b32 exec_lo, s22
	s_mov_b32 exec_hi, 0
	s_cbranch_execz .Lsplit1_join
	v_mov_b32_e32 v240, 0x7000
	v_mov_b32_e32 v242, 0
.Lsplit1_spin:
	global_load_dword v241, v240, s[82:83] offset:1280 sc1
	s_waitcnt vmcnt(0)
	v_add_u32_e32 v242, 1, v242
	v_readfirstlane_b32 s22, v241
	s_nop 3
	s_cmp_ge_u32 s22, 1
	s_cbranch_scc1 .Lsplit1_join
	s_sleep 1
	v_readfirstlane_b32 s22, v242
	s_nop 3
	s_cmp_lt_u32 s22, 0x40001
	s_cbranch_scc1 .Lsplit1_spin
	v_mov_b32_e32 v241, 1
	v_mov_b32_e32 v242, 0x4000
	global_atomic_add v242, v241, s[82:83] offset:512
	s_waitcnt vmcnt(0)
.Lsplit1_join:
	s_mov_b64 exec, s[20:21]
	v_mov_b32_e32 v209, v0
	s_waitcnt lgkmcnt(0)
	s_barrier
	s_lshl_b32 s29, s64, 3
	v_readfirstlane_b32 s0, v209
	s_ashr_i32 s28, s0, 6
	s_add_i32 s0, s28, s29
	s_cmpk_lt_i32 s0, 0x4000
	v_and_b32_e32 v208, 63, v209
	s_cselect_b64 s[4:5], -1, 0
	s_and_b64 vcc, exec, s[4:5]
	v_lshlrev_b32_e32 v200, 4, v208
	s_cbranch_vccz .LBB0_66
	s_ashr_i32 s1, s0, 31
	s_lshl_b64 s[8:9], s[0:1], 12
	s_add_u32 s8, s44, s8
	s_addc_u32 s9, s45, s9
	global_load_dwordx4 v[6:9], v200, s[8:9] nt
	global_load_dwordx4 v[2:5], v200, s[8:9] offset:1024 nt
	global_load_dwordx4 v[14:17], v200, s[8:9] offset:2048 nt
	global_load_dwordx4 v[10:13], v200, s[8:9] offset:3072 nt

.LBB0_116:
	v_readlane_b32 s63, v254, 2
.LBB0_119:
	s_waitcnt vmcnt(0)
	s_waitcnt lgkmcnt(0)
	s_barrier
	s_mov_b64 s[0:1], exec
	v_readlane_b32 s2, v254, 6
	v_readlane_b32 s3, v254, 7
	s_and_b64 s[2:3], s[0:1], s[2:3]
	s_mov_b64 exec, s[2:3]
	s_cbranch_execz .LBB0_171
	s_add_i32 s2, 0, 0x26d60
	v_mov_b32_e32 v2, s2
	s_waitcnt vmcnt(0) expcnt(0) lgkmcnt(0)
	ds_read_b32 v4, v2
	s_add_i32 s2, 0, 0x26d64
	v_mov_b32_e32 v2, s2
	ds_read_b32 v2, v2
	s_waitcnt lgkmcnt(1)
	v_cmp_ne_u32_e32 vcc, 0, v4
	s_cbranch_vccnz .LBB0_135
	v_readlane_b32 s2, v254, 0
	v_readlane_b32 s3, v254, 1
	s_load_dwordx2 s[6:7], s[2:3], 0x4
	s_add_u32 s2, s82, 0x4200
	s_addc_u32 s3, s83, 0
	s_add_u32 s4, s82, 0x4400
	s_addc_u32 s5, s83, 0
	s_waitcnt lgkmcnt(0)
	s_mul_i32 s33, s6, s63
	s_add_u32 s6, s82, 0x4500
	s_mul_i32 s33, s33, s7
	s_addc_u32 s7, s83, 0
	s_add_u32 s8, s82, 0x4600
	s_addc_u32 s9, s83, 0
	s_add_u32 s10, s82, 0x4700
	s_addc_u32 s11, s83, 0
	s_add_u32 s12, s82, 0x4800
	s_addc_u32 s13, s83, 0
	s_add_u32 s14, s82, 0x4900
	s_addc_u32 s15, s83, 0
	s_add_u32 s16, s82, 0x4a00
	s_addc_u32 s17, s83, 0
	s_add_u32 s18, s82, 0x4b00
	s_addc_u32 s19, s83, 0
	s_add_u32 s20, s82, 0x4c00
	s_addc_u32 s21, s83, 0
	s_add_u32 s22, s82, 0x4d00
	s_addc_u32 s23, s83, 0
	s_add_u32 s28, s82, 0x4e00
	s_addc_u32 s29, s83, 0
	s_add_u32 s30, s82, 0x4f00
	s_addc_u32 s31, s83, 0
	s_add_u32 s34, s82, 0x5000
	s_addc_u32 s35, s83, 0
	s_add_u32 s36, s82, 0x5100
	s_addc_u32 s37, s83, 0
	s_add_u32 s38, s82, 0x5200
	s_addc_u32 s39, s83, 0
	s_add_u32 s40, s82, 0x5300
	s_addc_u32 s41, s83, 0
	s_mov_b32 s48, 1
	v_mov_b32_e32 v18, 0
	s_branch .LBB0_123

.LBB0_833:
	v_max_i32_e32 v2, 0, v6
	v_lshlrev_b64 v[8:9], 7, v[2:3]
	s_mov_b32 m0, s85
	v_lshl_add_u64 v[8:9], v[4:5], 0, v[8:9]
	global_load_lds_dwordx4 v[8:9], off
	s_add_i32 s7, s7, 1
	s_addk_i32 s85, 0x2000
	s_cmp_gt_u32 s7, 10
	v_add_u32_e32 v6, 32, v6
	s_cbranch_scc0 .LBB0_833
	s_lshl_b64 s[76:77], s[76:77], 1
	s_add_u32 s76, s93, s76
	s_addc_u32 s77, s94, s77
	s_add_i32 s7, s8, s88
	v_or_b32_e32 v4, s7, v197
	v_ashrrev_i32_e32 v5, 31, v4
	v_lshlrev_b64 v[4:5], 7, v[4:5]
	v_lshl_add_u64 v[4:5], s[76:77], 0, v[4:5]
	v_or_b32_e32 v192, s7, v196
	s_and_b32 s76, s84, 0x3fffffc0
	v_lshl_add_u64 v[4:5], v[4:5], 0, v[190:191]
	s_lshl_b32 s85, s74, 4
	s_lshl_b32 s76, s76, 1
	s_mov_b32 s77, s75
	v_lshl_or_b32 v2, s74, 2, v198
	v_ashrrev_i32_e32 v8, 2, v192
	global_load_dwordx4 v[94:97], v[4:5], off
	global_load_dwordx4 v[90:93], v[4:5], off offset:32
	global_load_dwordx4 v[86:89], v[4:5], off offset:64
	global_load_dwordx4 v[82:85], v[4:5], off offset:96
	s_cmp_lg_u32 s6, 0
	s_cbranch_scc1 .Lb5_merge_here
	v_ashrrev_i32_e32 v193, 31, v192
	s_cmp_ge_i32 s33, s9
	s_branch .Lb5_merge_skip

.Lb5_merge_skip:
	s_waitcnt vmcnt(0)
	s_cselect_b64 s[76:77], -1, 0
	s_and_b64 vcc, exec, s[76:77]
	v_add_u32_e32 v34, v209, v202
	v_add_u32_e32 v35, v209, v201
	v_add_u32_e32 v36, v209, v200
	s_waitcnt vmcnt(0) lgkmcnt(0)
	s_barrier
	s_cbranch_vccz .LBB0_836
	ds_read_b128 v[4:7], v221
	ds_read_b128 v[8:11], v34
	ds_read_b128 v[12:15], v35
	ds_read_b128 v[16:19], v36
	s_waitcnt lgkmcnt(0)
	v_mfma_f32_32x32x16_bf16 v[18:33], v[16:19], v[94:97], 0
	v_add_u32_e32 v2, s95, v204
	ds_read_b64_tr_b16 v[146:147], v2 offset:4096
	ds_read_b64_tr_b16 v[148:149], v2 offset:5120
	ds_read_b64_tr_b16 v[150:151], v2 offset:6144
	ds_read_b64_tr_b16 v[152:153], v2 offset:7168
	v_add_u32_e32 v2, s95, v205
	ds_read_b64_tr_b16 v[158:159], v2 offset:4096
	ds_read_b64_tr_b16 v[160:161], v2 offset:5120
	ds_read_b64_tr_b16 v[154:155], v2 offset:6144
	ds_read_b64_tr_b16 v[156:157], v2 offset:7168
	v_mfma_f32_32x32x16_bf16 v[18:33], v[12:15], v[90:93], v[18:33]
	v_mfma_f32_32x32x16_bf16 v[18:33], v[8:11], v[86:89], v[18:33]
	v_mfma_f32_32x32x16_bf16 v[18:33], v[4:7], v[82:85], v[18:33]
	s_branch .LBB0_837

.LBB0_841:
	s_cmp_lg_u32 s6, 0
	s_cbranch_scc1 .Lb5mid_go
	s_mov_b64 s[98:99], exec
	v_readlane_b32 s100, v254, 6
	v_readlane_b32 s101, v254, 7
	s_and_b64 s[100:101], s[98:99], s[100:101]
	s_mov_b64 exec, s[100:101]
	s_cbranch_execz .Lsplit5_join
	v_mov_b32_e32 v240, 0x7000
	s_mov_b32 s100, 0

.Lsplit5_join:
	s_mov_b64 exec, s[98:99]
	s_barrier
	s_and_b32 s98, s84, 0x3fffffc0
	s_lshl_b32 s98, s98, 1
	s_mov_b32 s99, 0
	v_lshl_or_b32 v234, s74, 2, v198
	v_mov_b32_e32 v235, 0
	v_ashrrev_i32_e32 v240, 2, v192
	v_lshl_add_u64 v[236:237], v[184:185], 0, s[98:99]
	v_lshlrev_b64 v[238:239], 12, v[234:235]
	v_ashrrev_i32_e32 v241, 31, v240
	v_or_b32_e32 v234, s85, v196
	s_ashr_i32 s98, s7, 4
	v_lshl_add_u64 v[240:241], v[238:239], 0, v[240:241]
	v_lshlrev_b64 v[242:243], 10, v[234:235]
	s_ashr_i32 s99, s98, 31
	v_lshl_add_u64 v[244:245], v[242:243], 0, s[98:99]
	v_lshlrev_b64 v[246:247], 7, v[240:241]
	v_lshl_add_u64 v[246:247], v[180:181], 0, v[246:247]
	v_lshlrev_b64 v[248:249], 7, v[244:245]
	v_ashrrev_i32_e32 v193, 31, v192
	v_lshl_add_u64 v[248:249], v[182:183], 0, v[248:249]
	global_load_dwordx4 v[142:145], v[246:247], off
	global_load_dwordx4 v[138:141], v[248:249], off
	v_lshlrev_b64 v[246:247], 10, v[192:193]
	v_lshl_add_u64 v[244:245], v[244:245], 2, s[0:1]
	v_lshl_add_u64 v[246:247], v[236:237], 0, v[246:247]
	v_lshl_add_u64 v[240:241], v[240:241], 2, s[0:1]
	v_add_co_u32_e32 v244, vcc, s4, v244
	s_nop 0
	v_addc_co_u32_e32 v245, vcc, 0, v245, vcc
	global_load_dwordx4 v[134:137], v[246:247], off
	global_load_dword v230, v[240:241], off
	global_load_dword v231, v[244:245], off
	v_or_b32_e32 v240, 8, v192
	v_ashrrev_i32_e32 v244, 2, v240
	v_and_or_b32 v234, v240, 15, s85
	v_ashrrev_i32_e32 v245, 31, v244
	v_lshlrev_b64 v[246:247], 10, v[234:235]
	v_lshl_add_u64 v[244:245], v[238:239], 0, v[244:245]
	v_lshl_add_u64 v[246:247], v[246:247], 0, s[98:99]
	v_ashrrev_i32_e32 v241, 31, v240
	v_lshlrev_b64 v[248:249], 7, v[244:245]
	v_lshlrev_b64 v[250:251], 7, v[246:247]
	v_lshlrev_b64 v[240:241], 10, v[240:241]
	v_lshl_add_u64 v[246:247], v[246:247], 2, s[0:1]
	v_lshl_add_u64 v[248:249], v[180:181], 0, v[248:249]
	v_lshl_add_u64 v[240:241], v[236:237], 0, v[240:241]
	v_add_co_u32_e32 v246, vcc, s4, v246
	v_lshl_add_u64 v[250:251], v[182:183], 0, v[250:251]
	global_load_dwordx4 v[130:133], v[248:249], off
	global_load_dwordx4 v[126:129], v[250:251], off
	v_lshl_add_u64 v[244:245], v[244:245], 2, s[0:1]
	v_addc_co_u32_e32 v247, vcc, 0, v247, vcc
	global_load_dwordx4 v[122:125], v[240:241], off
	global_load_dword v228, v[244:245], off
	global_load_dword v229, v[246:247], off
	v_or_b32_e32 v240, 16, v192
	v_ashrrev_i32_e32 v244, 2, v240
	v_ashrrev_i32_e32 v246, 4, v240
	v_ashrrev_i32_e32 v245, 31, v244
	v_ashrrev_i32_e32 v247, 31, v246
	v_lshl_add_u64 v[244:245], v[238:239], 0, v[244:245]
	v_lshl_add_u64 v[242:243], v[242:243], 0, v[246:247]
	v_ashrrev_i32_e32 v241, 31, v240
	v_lshlrev_b64 v[246:247], 7, v[244:245]
	v_lshlrev_b64 v[248:249], 7, v[242:243]
	v_lshlrev_b64 v[240:241], 10, v[240:241]
	v_lshl_add_u64 v[242:243], v[242:243], 2, s[0:1]
	v_lshl_add_u64 v[246:247], v[180:181], 0, v[246:247]
	v_lshl_add_u64 v[240:241], v[236:237], 0, v[240:241]
	v_add_co_u32_e32 v242, vcc, s4, v242
	v_lshl_add_u64 v[248:249], v[182:183], 0, v[248:249]
	global_load_dwordx4 v[118:121], v[246:247], off
	global_load_dwordx4 v[114:117], v[248:249], off
	v_lshl_add_u64 v[244:245], v[244:245], 2, s[0:1]
	v_addc_co_u32_e32 v243, vcc, 0, v243, vcc
	global_load_dwordx4 v[110:113], v[240:241], off
	global_load_dword v226, v[244:245], off
	global_load_dword v227, v[242:243], off
	v_or_b32_e32 v240, 24, v192
	v_ashrrev_i32_e32 v242, 2, v240
	v_ashrrev_i32_e32 v243, 31, v242
	v_and_or_b32 v234, v240, 15, s85
	v_ashrrev_i32_e32 v244, 4, v240
	v_lshl_add_u64 v[238:239], v[238:239], 0, v[242:243]
	v_lshlrev_b64 v[242:243], 10, v[234:235]
	v_ashrrev_i32_e32 v245, 31, v244
	v_ashrrev_i32_e32 v241, 31, v240
	v_lshl_add_u64 v[242:243], v[242:243], 0, v[244:245]
	v_lshlrev_b64 v[240:241], 10, v[240:241]
	v_lshlrev_b64 v[244:245], 7, v[238:239]
	v_lshl_add_u64 v[236:237], v[236:237], 0, v[240:241]
	v_lshl_add_u64 v[240:241], v[242:243], 2, s[0:1]
	v_lshl_add_u64 v[244:245], v[180:181], 0, v[244:245]
	v_lshlrev_b64 v[246:247], 7, v[242:243]
	v_add_co_u32_e32 v240, vcc, 0x80000, v240
	v_lshl_add_u64 v[246:247], v[182:183], 0, v[246:247]
	global_load_dwordx4 v[106:109], v[244:245], off
	global_load_dwordx4 v[102:105], v[246:247], off
	v_lshl_add_u64 v[238:239], v[238:239], 2, s[0:1]
	v_addc_co_u32_e32 v241, vcc, 0, v241, vcc
	global_load_dwordx4 v[98:101], v[236:237], off
	global_load_dword v224, v[238:239], off
	global_load_dword v225, v[240:241], off

.LBB0_867:
	s_or_b64 exec, exec, s[76:77]
	s_waitcnt vmcnt(0)
	s_waitcnt lgkmcnt(0)
	ds_read_b32 v2, v216 offset:4608
	ds_read_b128 v[14:17], v215
	global_load_dwordx4 v[4:7], v[188:189], off
	v_and_b32_e32 v25, 0xffff0000, v145
	v_lshlrev_b32_e32 v22, 16, v145
	s_waitcnt lgkmcnt(1)
	v_max3_f32 v8, v2, v230, v231
	v_sub_f32_e32 v2, v2, v8
	v_sub_f32_e32 v9, v230, v8
	v_sub_f32_e32 v8, v231, v8
	v_exp_f32_e32 v18, v9
	v_exp_f32_e32 v20, v8
	global_load_dwordx4 v[8:11], v[188:189], off offset:16
	v_exp_f32_e32 v19, v2
	s_waitcnt lgkmcnt(0)
	v_lshlrev_b32_e32 v24, 16, v17
	v_and_b32_e32 v23, 0xffff0000, v17
	v_and_b32_e32 v17, 0xffff0000, v144
	v_add_f32_e32 v2, v19, v18
	v_add_f32_e32 v2, v20, v2
	v_rcp_f32_e32 v2, v2
	v_lshlrev_b32_e32 v26, 16, v140
	v_and_b32_e32 v27, 0xffff0000, v140
	v_lshlrev_b32_e32 v30, 16, v139
	v_pk_mul_f32 v[18:19], v[18:19], v[2:3] op_sel_hi:[1,0]
	v_mul_f32_e32 v20, v20, v2
	v_pk_mul_f32 v[24:25], v[18:19], v[24:25] op_sel:[1,0] op_sel_hi:[0,1]
	v_pk_fma_f32 v[22:23], v[18:19], v[22:23], v[24:25]
	v_lshlrev_b32_e32 v24, 16, v141
	v_and_b32_e32 v25, 0xffff0000, v141
	v_pk_fma_f32 v[22:23], v[20:21], v[24:25], v[22:23] op_sel_hi:[0,1,1]
	v_and_b32_e32 v25, 0xffff0000, v16
	v_lshlrev_b32_e32 v16, 16, v16
	v_lshlrev_b32_e32 v24, 16, v144
	v_pk_mul_f32 v[16:17], v[18:19], v[16:17] op_sel:[1,0] op_sel_hi:[0,1]
	v_pk_fma_f32 v[16:17], v[18:19], v[24:25], v[16:17]
	v_lshlrev_b32_e32 v24, 16, v143
	v_pk_fma_f32 v[16:17], v[20:21], v[26:27], v[16:17] op_sel_hi:[0,1,1]
	v_lshlrev_b32_e32 v26, 16, v15
	v_and_b32_e32 v27, 0xffff0000, v143
	v_and_b32_e32 v25, 0xffff0000, v15
	v_pk_mul_f32 v[26:27], v[18:19], v[26:27] op_sel:[1,0] op_sel_hi:[0,1]
	v_pk_fma_f32 v[24:25], v[18:19], v[24:25], v[26:27]
	v_and_b32_e32 v27, 0xffff0000, v14
	v_lshlrev_b32_e32 v14, 16, v14
	v_and_b32_e32 v15, 0xffff0000, v142
	v_and_b32_e32 v31, 0xffff0000, v139
	v_lshlrev_b32_e32 v26, 16, v142
	v_pk_mul_f32 v[14:15], v[18:19], v[14:15] op_sel:[1,0] op_sel_hi:[0,1]
	v_pk_fma_f32 v[24:25], v[20:21], v[30:31], v[24:25] op_sel_hi:[0,1,1]
	v_lshlrev_b32_e32 v30, 16, v138
	v_and_b32_e32 v31, 0xffff0000, v138
	v_pk_fma_f32 v[14:15], v[18:19], v[26:27], v[14:15]
	v_mov_b32_e32 v18, v24
	v_pk_fma_f32 v[14:15], v[20:21], v[30:31], v[14:15] op_sel_hi:[0,1,1]
	v_mov_b32_e32 v20, v25
	v_mov_b32_e32 v21, v23
	v_mov_b32_e32 v19, v22
	v_pk_mul_f32 v[20:21], v[20:21], v[20:21]
	v_mov_b32_e32 v26, v15
	v_mov_b32_e32 v27, v17
	v_pk_fma_f32 v[18:19], v[18:19], v[18:19], v[20:21]
	v_mov_b32_e32 v20, v14
	v_mov_b32_e32 v21, v16
	v_pk_mul_f32 v[26:27], v[26:27], v[26:27]
	v_lshlrev_b32_e32 v32, 16, v135
	v_pk_fma_f32 v[20:21], v[20:21], v[20:21], v[26:27]
	v_and_b32_e32 v33, 0xffff0000, v135
	v_pk_add_f32 v[18:19], v[20:21], v[18:19]
	s_add_i32 s74, s74, 8
	v_add_f32_e32 v2, v18, v19
	v_lshlrev_b32_e32 v18, 16, v134
	v_and_b32_e32 v19, 0xffff0000, v134
	v_add_f32_dpp v2, v2, v2 quad_perm:[1,0,3,2] row_mask:0xf bank_mask:0xf bound_ctrl:1
	v_lshlrev_b32_e32 v28, 16, v136
	v_and_b32_e32 v29, 0xffff0000, v136
	v_add_f32_dpp v2, v2, v2 quad_perm:[2,3,0,1] row_mask:0xf bank_mask:0xf bound_ctrl:1
	v_lshlrev_b32_e32 v20, 16, v137
	v_and_b32_e32 v21, 0xffff0000, v137
	v_add_f32_dpp v2, v2, v2 row_half_mirror row_mask:0xf bank_mask:0xf bound_ctrl:1
	v_fmamk_f32 v2, v2, 0x3c800000, v217
	v_rsq_f32_e32 v2, v2
	s_lshl_b64 s[76:77], s[74:75], 21
	v_lshl_add_u64 v[12:13], v[186:187], 0, s[76:77]
	v_and_b32_e32 v27, 0xffff0000, v133
	v_pk_mul_f32 v[14:15], v[14:15], v[2:3] op_sel_hi:[1,0]
	v_pk_mul_f32 v[16:17], v[16:17], v[2:3] op_sel_hi:[1,0]
	s_waitcnt vmcnt(1)
	v_pk_mul_f32 v[14:15], v[4:5], v[14:15]
	v_lshlrev_b32_e32 v34, 16, v123
	v_pk_mul_f32 v[14:15], v[14:15], v[18:19]
	v_pk_mul_f32 v[18:19], v[24:25], v[2:3] op_sel_hi:[1,0]
	v_cvt_pk_bf16_f32 v14, v14, v15
	v_pk_mul_f32 v[18:19], v[6:7], v[18:19]
	s_waitcnt vmcnt(0)
	v_pk_mul_f32 v[16:17], v[8:9], v[16:17]
	v_pk_mul_f32 v[18:19], v[18:19], v[32:33]
	v_pk_mul_f32 v[16:17], v[16:17], v[28:29]
	v_cvt_pk_bf16_f32 v15, v18, v19
	v_pk_mul_f32 v[18:19], v[22:23], v[2:3] op_sel_hi:[1,0]
	v_cvt_pk_bf16_f32 v16, v16, v17
	v_pk_mul_f32 v[18:19], v[10:11], v[18:19]
	v_lshlrev_b32_e32 v24, 16, v133
	v_pk_mul_f32 v[18:19], v[18:19], v[20:21]
	v_lshlrev_b32_e32 v28, 16, v128
	v_cvt_pk_bf16_f32 v17, v18, v19
	v_lshlrev_b64 v[18:19], 7, v[192:193]
	v_lshl_add_u64 v[18:19], v[12:13], 0, v[18:19]
	global_store_dwordx4 v[18:19], v[14:17], off sc1
	s_nop 1
	ds_read_b32 v2, v218 offset:4608
	ds_read_b128 v[14:17], v215 offset:1152
	v_and_b32_e32 v29, 0xffff0000, v128
	v_lshlrev_b32_e32 v32, 16, v127
	v_and_b32_e32 v33, 0xffff0000, v127
	s_waitcnt lgkmcnt(1)
	v_max3_f32 v20, v2, v228, v229
	v_sub_f32_e32 v2, v2, v20
	v_exp_f32_e32 v19, v2
	v_sub_f32_e32 v2, v228, v20
	v_exp_f32_e32 v18, v2
	v_sub_f32_e32 v2, v229, v20
	v_exp_f32_e32 v21, v2
	s_waitcnt lgkmcnt(0)
	v_lshlrev_b32_e32 v26, 16, v17
	v_add_f32_e32 v2, v19, v18
	v_and_b32_e32 v25, 0xffff0000, v17
	v_add_f32_e32 v2, v21, v2
	v_rcp_f32_e32 v2, v2
	v_and_b32_e32 v17, 0xffff0000, v132
	v_and_b32_e32 v35, 0xffff0000, v123
	v_or_b32_e32 v20, s7, v206
	v_pk_mul_f32 v[18:19], v[18:19], v[2:3] op_sel_hi:[1,0]
	v_mul_f32_e32 v22, v21, v2
	v_pk_mul_f32 v[26:27], v[18:19], v[26:27] op_sel:[1,0] op_sel_hi:[0,1]
	v_pk_fma_f32 v[24:25], v[18:19], v[24:25], v[26:27]
	v_lshlrev_b32_e32 v26, 16, v129
	v_and_b32_e32 v27, 0xffff0000, v129
	v_pk_fma_f32 v[24:25], v[22:23], v[26:27], v[24:25] op_sel_hi:[0,1,1]
	v_and_b32_e32 v27, 0xffff0000, v16
	v_lshlrev_b32_e32 v16, 16, v16
	v_lshlrev_b32_e32 v26, 16, v132
	v_pk_mul_f32 v[16:17], v[18:19], v[16:17] op_sel:[1,0] op_sel_hi:[0,1]
	v_pk_fma_f32 v[16:17], v[18:19], v[26:27], v[16:17]
	v_lshlrev_b32_e32 v26, 16, v131
	v_pk_fma_f32 v[16:17], v[22:23], v[28:29], v[16:17] op_sel_hi:[0,1,1]
	v_lshlrev_b32_e32 v28, 16, v15
	v_and_b32_e32 v29, 0xffff0000, v131
	v_and_b32_e32 v27, 0xffff0000, v15
	v_pk_mul_f32 v[28:29], v[18:19], v[28:29] op_sel:[1,0] op_sel_hi:[0,1]
	v_pk_fma_f32 v[26:27], v[18:19], v[26:27], v[28:29]
	v_and_b32_e32 v29, 0xffff0000, v14
	v_lshlrev_b32_e32 v14, 16, v14
	v_and_b32_e32 v15, 0xffff0000, v130
	v_lshlrev_b32_e32 v28, 16, v130
	v_pk_mul_f32 v[14:15], v[18:19], v[14:15] op_sel:[1,0] op_sel_hi:[0,1]
	v_pk_fma_f32 v[26:27], v[22:23], v[32:33], v[26:27] op_sel_hi:[0,1,1]
	v_lshlrev_b32_e32 v32, 16, v126
	v_and_b32_e32 v33, 0xffff0000, v126
	v_pk_fma_f32 v[14:15], v[18:19], v[28:29], v[14:15]
	v_mov_b32_e32 v18, v26
	v_pk_fma_f32 v[14:15], v[22:23], v[32:33], v[14:15] op_sel_hi:[0,1,1]
	v_mov_b32_e32 v22, v27
	v_mov_b32_e32 v23, v25
	v_mov_b32_e32 v19, v24
	v_pk_mul_f32 v[22:23], v[22:23], v[22:23]
	v_mov_b32_e32 v28, v15
	v_mov_b32_e32 v29, v17
	v_pk_fma_f32 v[18:19], v[18:19], v[18:19], v[22:23]
	v_mov_b32_e32 v22, v14
	v_mov_b32_e32 v23, v16
	v_pk_mul_f32 v[28:29], v[28:29], v[28:29]
	v_lshlrev_b32_e32 v30, 16, v124
	v_pk_fma_f32 v[22:23], v[22:23], v[22:23], v[28:29]
	v_and_b32_e32 v31, 0xffff0000, v124
	v_pk_add_f32 v[18:19], v[22:23], v[18:19]
	v_lshlrev_b32_e32 v22, 16, v125
	v_add_f32_e32 v2, v18, v19
	v_lshlrev_b32_e32 v18, 16, v122
	v_and_b32_e32 v19, 0xffff0000, v122
	v_add_f32_dpp v2, v2, v2 quad_perm:[1,0,3,2] row_mask:0xf bank_mask:0xf bound_ctrl:1
	v_and_b32_e32 v23, 0xffff0000, v125
	v_ashrrev_i32_e32 v21, 31, v20
	v_add_f32_dpp v2, v2, v2 quad_perm:[2,3,0,1] row_mask:0xf bank_mask:0xf bound_ctrl:1
	v_lshlrev_b32_e32 v28, 16, v116
	v_and_b32_e32 v29, 0xffff0000, v116
	v_add_f32_dpp v2, v2, v2 row_half_mirror row_mask:0xf bank_mask:0xf bound_ctrl:1
	v_fmamk_f32 v2, v2, 0x3c800000, v217
	v_rsq_f32_e32 v2, v2
	v_lshlrev_b32_e32 v32, 16, v115
	v_and_b32_e32 v33, 0xffff0000, v115
	v_pk_mul_f32 v[14:15], v[14:15], v[2:3] op_sel_hi:[1,0]
	s_nop 0
	v_pk_mul_f32 v[14:15], v[4:5], v[14:15]
	v_pk_mul_f32 v[16:17], v[16:17], v[2:3] op_sel_hi:[1,0]
	v_pk_mul_f32 v[14:15], v[14:15], v[18:19]
	v_pk_mul_f32 v[18:19], v[26:27], v[2:3] op_sel_hi:[1,0]
	v_cvt_pk_bf16_f32 v14, v14, v15
	v_pk_mul_f32 v[18:19], v[6:7], v[18:19]
	v_pk_mul_f32 v[16:17], v[8:9], v[16:17]
	v_pk_mul_f32 v[18:19], v[18:19], v[34:35]
	v_pk_mul_f32 v[16:17], v[16:17], v[30:31]
	v_cvt_pk_bf16_f32 v15, v18, v19
	v_pk_mul_f32 v[18:19], v[24:25], v[2:3] op_sel_hi:[1,0]
	v_cvt_pk_bf16_f32 v16, v16, v17
	v_pk_mul_f32 v[18:19], v[10:11], v[18:19]
	v_and_b32_e32 v27, 0xffff0000, v121
	v_pk_mul_f32 v[18:19], v[18:19], v[22:23]
	v_lshlrev_b32_e32 v24, 16, v121
	v_cvt_pk_bf16_f32 v17, v18, v19
	v_lshlrev_b64 v[18:19], 7, v[20:21]
	v_lshl_add_u64 v[18:19], v[12:13], 0, v[18:19]
	global_store_dwordx4 v[18:19], v[14:17], off sc1
	s_nop 1
	ds_read_b32 v2, v219 offset:4608
	ds_read_b128 v[14:17], v215 offset:2304
	v_lshlrev_b32_e32 v34, 16, v111
	v_and_b32_e32 v35, 0xffff0000, v111
	v_lshlrev_b32_e32 v30, 16, v112
	s_waitcnt lgkmcnt(1)
	v_max3_f32 v20, v2, v226, v227
	v_sub_f32_e32 v2, v2, v20
	v_exp_f32_e32 v19, v2
	v_sub_f32_e32 v2, v226, v20
	v_exp_f32_e32 v18, v2
	v_sub_f32_e32 v2, v227, v20
	v_exp_f32_e32 v21, v2
	s_waitcnt lgkmcnt(0)
	v_lshlrev_b32_e32 v26, 16, v17
	v_add_f32_e32 v2, v19, v18
	v_and_b32_e32 v25, 0xffff0000, v17
	v_add_f32_e32 v2, v21, v2
	v_rcp_f32_e32 v2, v2
	v_and_b32_e32 v17, 0xffff0000, v120
	v_or_b32_e32 v20, s7, v207
	v_and_b32_e32 v31, 0xffff0000, v112
	v_pk_mul_f32 v[18:19], v[18:19], v[2:3] op_sel_hi:[1,0]
	v_mul_f32_e32 v22, v21, v2
	v_pk_mul_f32 v[26:27], v[18:19], v[26:27] op_sel:[1,0] op_sel_hi:[0,1]
	v_pk_fma_f32 v[24:25], v[18:19], v[24:25], v[26:27]
	v_lshlrev_b32_e32 v26, 16, v117
	v_and_b32_e32 v27, 0xffff0000, v117
	v_pk_fma_f32 v[24:25], v[22:23], v[26:27], v[24:25] op_sel_hi:[0,1,1]
	v_and_b32_e32 v27, 0xffff0000, v16
	v_lshlrev_b32_e32 v16, 16, v16
	v_lshlrev_b32_e32 v26, 16, v120
	v_pk_mul_f32 v[16:17], v[18:19], v[16:17] op_sel:[1,0] op_sel_hi:[0,1]
	v_pk_fma_f32 v[16:17], v[18:19], v[26:27], v[16:17]
	v_lshlrev_b32_e32 v26, 16, v119
	v_pk_fma_f32 v[16:17], v[22:23], v[28:29], v[16:17] op_sel_hi:[0,1,1]
	v_lshlrev_b32_e32 v28, 16, v15
	v_and_b32_e32 v29, 0xffff0000, v119
	v_and_b32_e32 v27, 0xffff0000, v15
	v_pk_mul_f32 v[28:29], v[18:19], v[28:29] op_sel:[1,0] op_sel_hi:[0,1]
	v_pk_fma_f32 v[26:27], v[18:19], v[26:27], v[28:29]
	v_and_b32_e32 v29, 0xffff0000, v14
	v_lshlrev_b32_e32 v14, 16, v14
	v_and_b32_e32 v15, 0xffff0000, v118
	v_lshlrev_b32_e32 v28, 16, v118
	v_pk_mul_f32 v[14:15], v[18:19], v[14:15] op_sel:[1,0] op_sel_hi:[0,1]
	v_pk_fma_f32 v[26:27], v[22:23], v[32:33], v[26:27] op_sel_hi:[0,1,1]
	v_lshlrev_b32_e32 v32, 16, v114
	v_and_b32_e32 v33, 0xffff0000, v114
	v_pk_fma_f32 v[14:15], v[18:19], v[28:29], v[14:15]
	v_mov_b32_e32 v18, v26
	v_pk_fma_f32 v[14:15], v[22:23], v[32:33], v[14:15] op_sel_hi:[0,1,1]
	v_mov_b32_e32 v22, v27
	v_mov_b32_e32 v23, v25
	v_mov_b32_e32 v19, v24
	v_pk_mul_f32 v[22:23], v[22:23], v[22:23]
	v_mov_b32_e32 v28, v15
	v_mov_b32_e32 v29, v17
	v_pk_fma_f32 v[18:19], v[18:19], v[18:19], v[22:23]
	v_mov_b32_e32 v22, v14
	v_mov_b32_e32 v23, v16
	v_pk_mul_f32 v[28:29], v[28:29], v[28:29]
	v_ashrrev_i32_e32 v21, 31, v20
	v_pk_fma_f32 v[22:23], v[22:23], v[22:23], v[28:29]
	v_lshlrev_b32_e32 v28, 16, v104
	v_pk_add_f32 v[18:19], v[22:23], v[18:19]
	v_lshlrev_b32_e32 v22, 16, v113
	v_add_f32_e32 v2, v18, v19
	v_lshlrev_b32_e32 v18, 16, v110
	v_and_b32_e32 v19, 0xffff0000, v110
	v_add_f32_dpp v2, v2, v2 quad_perm:[1,0,3,2] row_mask:0xf bank_mask:0xf bound_ctrl:1
	v_and_b32_e32 v23, 0xffff0000, v113
	v_and_b32_e32 v29, 0xffff0000, v104
	v_add_f32_dpp v2, v2, v2 quad_perm:[2,3,0,1] row_mask:0xf bank_mask:0xf bound_ctrl:1
	v_lshlrev_b32_e32 v32, 16, v103
	v_and_b32_e32 v33, 0xffff0000, v103
	v_add_f32_dpp v2, v2, v2 row_half_mirror row_mask:0xf bank_mask:0xf bound_ctrl:1
	v_fmamk_f32 v2, v2, 0x3c800000, v217
	v_rsq_f32_e32 v2, v2
	s_nop 0
	v_pk_mul_f32 v[14:15], v[14:15], v[2:3] op_sel_hi:[1,0]
	s_nop 0
	v_pk_mul_f32 v[14:15], v[4:5], v[14:15]
	v_pk_mul_f32 v[16:17], v[16:17], v[2:3] op_sel_hi:[1,0]
	v_pk_mul_f32 v[14:15], v[14:15], v[18:19]
	v_pk_mul_f32 v[18:19], v[26:27], v[2:3] op_sel_hi:[1,0]
	v_cvt_pk_bf16_f32 v14, v14, v15
	v_pk_mul_f32 v[18:19], v[6:7], v[18:19]
	v_pk_mul_f32 v[16:17], v[8:9], v[16:17]
	v_pk_mul_f32 v[18:19], v[18:19], v[34:35]
	v_pk_mul_f32 v[16:17], v[16:17], v[30:31]
	v_cvt_pk_bf16_f32 v15, v18, v19
	v_pk_mul_f32 v[18:19], v[24:25], v[2:3] op_sel_hi:[1,0]
	v_cvt_pk_bf16_f32 v16, v16, v17
	v_pk_mul_f32 v[18:19], v[10:11], v[18:19]
	v_and_b32_e32 v27, 0xffff0000, v109
	v_pk_mul_f32 v[18:19], v[18:19], v[22:23]
	v_lshlrev_b32_e32 v24, 16, v109
	v_cvt_pk_bf16_f32 v17, v18, v19
	v_lshlrev_b64 v[18:19], 7, v[20:21]
	v_lshl_add_u64 v[18:19], v[12:13], 0, v[18:19]
	global_store_dwordx4 v[18:19], v[14:17], off sc1
	s_nop 1
	ds_read_b32 v2, v220 offset:4608
	ds_read_b128 v[14:17], v215 offset:3456
	v_lshlrev_b32_e32 v34, 16, v99
	v_and_b32_e32 v35, 0xffff0000, v99
	v_lshlrev_b32_e32 v30, 16, v100
	s_waitcnt lgkmcnt(1)
	v_max3_f32 v20, v2, v224, v225
	v_sub_f32_e32 v2, v2, v20
	v_exp_f32_e32 v19, v2
	v_sub_f32_e32 v2, v224, v20
	v_exp_f32_e32 v18, v2
	v_sub_f32_e32 v2, v225, v20
	v_exp_f32_e32 v21, v2
	s_waitcnt lgkmcnt(0)
	v_lshlrev_b32_e32 v26, 16, v17
	v_add_f32_e32 v2, v19, v18
	v_and_b32_e32 v25, 0xffff0000, v17
	v_add_f32_e32 v2, v21, v2
	v_rcp_f32_e32 v2, v2
	v_and_b32_e32 v17, 0xffff0000, v108
	v_or_b32_e32 v20, s7, v208
	v_and_b32_e32 v31, 0xffff0000, v100
	v_pk_mul_f32 v[18:19], v[18:19], v[2:3] op_sel_hi:[1,0]
	v_mul_f32_e32 v22, v21, v2
	v_pk_mul_f32 v[26:27], v[18:19], v[26:27] op_sel:[1,0] op_sel_hi:[0,1]
	v_pk_fma_f32 v[24:25], v[18:19], v[24:25], v[26:27]
	v_lshlrev_b32_e32 v26, 16, v105
	v_and_b32_e32 v27, 0xffff0000, v105
	v_pk_fma_f32 v[24:25], v[22:23], v[26:27], v[24:25] op_sel_hi:[0,1,1]
	v_and_b32_e32 v27, 0xffff0000, v16
	v_lshlrev_b32_e32 v16, 16, v16
	v_lshlrev_b32_e32 v26, 16, v108
	v_pk_mul_f32 v[16:17], v[18:19], v[16:17] op_sel:[1,0] op_sel_hi:[0,1]
	v_pk_fma_f32 v[16:17], v[18:19], v[26:27], v[16:17]
	v_lshlrev_b32_e32 v26, 16, v107
	v_pk_fma_f32 v[16:17], v[22:23], v[28:29], v[16:17] op_sel_hi:[0,1,1]
	v_lshlrev_b32_e32 v28, 16, v15
	v_and_b32_e32 v29, 0xffff0000, v107
	v_and_b32_e32 v27, 0xffff0000, v15
	v_pk_mul_f32 v[28:29], v[18:19], v[28:29] op_sel:[1,0] op_sel_hi:[0,1]
	v_pk_fma_f32 v[26:27], v[18:19], v[26:27], v[28:29]
	v_and_b32_e32 v29, 0xffff0000, v14
	v_lshlrev_b32_e32 v14, 16, v14
	v_and_b32_e32 v15, 0xffff0000, v106
	v_lshlrev_b32_e32 v28, 16, v106
	v_pk_mul_f32 v[14:15], v[18:19], v[14:15] op_sel:[1,0] op_sel_hi:[0,1]
	v_pk_fma_f32 v[26:27], v[22:23], v[32:33], v[26:27] op_sel_hi:[0,1,1]
	v_lshlrev_b32_e32 v32, 16, v102
	v_and_b32_e32 v33, 0xffff0000, v102
	v_pk_fma_f32 v[14:15], v[18:19], v[28:29], v[14:15]
	v_mov_b32_e32 v18, v26
	v_pk_fma_f32 v[14:15], v[22:23], v[32:33], v[14:15] op_sel_hi:[0,1,1]
	v_mov_b32_e32 v22, v27
	v_mov_b32_e32 v23, v25
	v_mov_b32_e32 v19, v24
	v_pk_mul_f32 v[22:23], v[22:23], v[22:23]
	v_mov_b32_e32 v28, v15
	v_mov_b32_e32 v29, v17
	v_pk_fma_f32 v[18:19], v[18:19], v[18:19], v[22:23]
	v_mov_b32_e32 v22, v14
	v_mov_b32_e32 v23, v16
	v_pk_mul_f32 v[28:29], v[28:29], v[28:29]
	v_ashrrev_i32_e32 v21, 31, v20
	v_pk_fma_f32 v[22:23], v[22:23], v[22:23], v[28:29]
	s_nop 0
	v_pk_add_f32 v[18:19], v[22:23], v[18:19]
	s_nop 0
	v_add_f32_e32 v2, v18, v19
	v_lshlrev_b32_e32 v18, 16, v98
	v_and_b32_e32 v19, 0xffff0000, v98
	v_add_f32_dpp v2, v2, v2 quad_perm:[1,0,3,2] row_mask:0xf bank_mask:0xf bound_ctrl:1
	s_nop 1
	v_add_f32_dpp v2, v2, v2 quad_perm:[2,3,0,1] row_mask:0xf bank_mask:0xf bound_ctrl:1
	s_nop 1
	v_add_f32_dpp v2, v2, v2 row_half_mirror row_mask:0xf bank_mask:0xf bound_ctrl:1
	v_fmamk_f32 v2, v2, 0x3c800000, v217
	v_rsq_f32_e32 v2, v2
	s_nop 0
	v_pk_mul_f32 v[14:15], v[14:15], v[2:3] op_sel_hi:[1,0]
	s_nop 0
	v_pk_mul_f32 v[4:5], v[4:5], v[14:15]
	v_pk_mul_f32 v[14:15], v[26:27], v[2:3] op_sel_hi:[1,0]
	v_pk_mul_f32 v[4:5], v[4:5], v[18:19]
	v_pk_mul_f32 v[6:7], v[6:7], v[14:15]
	v_cvt_pk_bf16_f32 v4, v4, v5
	v_pk_mul_f32 v[6:7], v[6:7], v[34:35]
	s_nop 0
	v_cvt_pk_bf16_f32 v5, v6, v7
	v_pk_mul_f32 v[6:7], v[16:17], v[2:3] op_sel_hi:[1,0]
	s_nop 0
	v_pk_mul_f32 v[6:7], v[8:9], v[6:7]
	v_pk_mul_f32 v[8:9], v[24:25], v[2:3] op_sel_hi:[1,0]
	v_pk_mul_f32 v[6:7], v[6:7], v[30:31]
	v_pk_mul_f32 v[8:9], v[10:11], v[8:9]
	v_lshlrev_b32_e32 v10, 16, v101
	v_and_b32_e32 v11, 0xffff0000, v101
	v_pk_mul_f32 v[8:9], v[8:9], v[10:11]
	v_cvt_pk_bf16_f32 v6, v6, v7
	v_cvt_pk_bf16_f32 v7, v8, v9
	v_lshlrev_b64 v[8:9], 7, v[20:21]
	v_lshl_add_u64 v[8:9], v[12:13], 0, v[8:9]
	global_store_dwordx4 v[8:9], v[4:7], off sc1
	s_nop 1
	s_waitcnt vmcnt(0)
	s_barrier
	s_mov_b64 s[76:77], exec
	v_readlane_b32 s84, v254, 6
	v_readlane_b32 s85, v254, 7
	s_and_b64 s[84:85], s[76:77], s[84:85]
	s_mov_b64 exec, s[84:85]
	s_cbranch_execz .LBB0_831
	s_mov_b64 s[84:85], exec
	v_mbcnt_lo_u32_b32 v2, s84, 0
	v_mbcnt_hi_u32_b32 v2, s85, v2
	v_cmp_eq_u32_e32 vcc, 0, v2
	s_and_b64 vcc, exec, vcc
	s_mov_b64 exec, vcc
	s_cbranch_execz .LBB0_831
	s_bcnt1_i32_b64 s7, s[84:85]
	v_mov_b32_e32 v2, s8
	v_readlane_b32 s8, v254, 44
	v_mov_b32_e32 v4, s7
	v_readlane_b32 s9, v254, 45
	s_nop 4
	global_atomic_add v2, v4, s[8:9]
	s_branch .LBB0_831
